# S1/S6 K-loops: first iteration peeled with zero C operand on each accumulator's first MFMA, removing 128 accumulator-zeroing moves per GEMM unit
# baseline (speedup 1.0000x reference)
;     __device__ bool next(int i, Unit& u) const { const int j = first + i * G; if (j >= count) return false; u.pm = j / nN; u.pn = j % nN; return true; }
; #define PG8_BAR __builtin_amdgcn_s_barrier()
; template <class Epi, class Sched, bool ALIGN_EPI = false, bool SP2 = false>
; __device__ __forceinline__ void gemm_phase(PG8_LAS unsigned char* lds, const Gemm g, const Sched& S, const Epi& E) {
;     ...
;     for (;;) {
;         const bool has_next = S.next(ui + 1, nxt);
;         const char* nA = has_next ? (const char*)g.A + (size_t)nxt.pm * tstep : cA; const char* nB = has_next ? (const char*)g.Bt + (size_t)nxt.pn * tstep : cB;
;         for (int t = 0; t < nt; t += 2) {
;             const bool last = (t == nt - 2);
;             const char* a1 = cA + (size_t)(t + 1) * kstep;
;             const char* a2 = last ? nA : cA + (size_t)(t + 2) * kstep; const char* b2 = last ? nB : cB + (size_t)(t + 2) * kstep;
;             const char* a3 = a2 + kstep; const char* b3 = b2 + kstep;
;             if (last && has_next) S.a_ready(nxt);
;             if constexpr (SP2) {
;             PG8_LDB(B0, 0, 0); PG8_LDB(B1, 0, 1); PG8_SCHED; PG8_LDA(At, 0, 0); PG8_STAGE(PG8_SA(1, 1), a1 + hstep, voffA);
;             PG8_WAIT_V(8); PG8_WAIT_L(0); PG8_BAR; PG8_MMA(0, 0, At, B0); PG8_MMA(0, 1, At, B1); PG8_BAR; PG8_SCHED;
;             PG8_LDA(At, 0, 1); PG8_STAGE(PG8_SB(0, 0), b2, voffB); PG8_STAGE(PG8_SB(0, 1), b2 + hstep, voffB); PG8_STAGE(PG8_SA(0, 0), a2, voffA);
;             PG8_WAIT_V(8); PG8_WAIT_L(0); PG8_BAR; PG8_MMA(1, 0, At, B0); PG8_MMA(1, 1, At, B1); PG8_BAR; PG8_SCHED;
;             PG8_LDB(B0, 1, 0); PG8_LDB(B1, 1, 1); PG8_SCHED; PG8_LDA(At, 1, 0); PG8_STAGE(PG8_SA(0, 1), a2 + hstep, voffA);
;             PG8_WAIT_V(8); PG8_WAIT_L(0); PG8_BAR; PG8_MMA(0, 0, At, B0); PG8_MMA(0, 1, At, B1); PG8_BAR; PG8_SCHED;
;             PG8_LDA(At, 1, 1); PG8_STAGE(PG8_SB(1, 0), b3, voffB); PG8_STAGE(PG8_SB(1, 1), b3 + hstep, voffB); PG8_STAGE(PG8_SA(1, 0), a3, voffA);
;             PG8_WAIT_V(8); PG8_WAIT_L(0); PG8_BAR; PG8_MMA(1, 0, At, B0); PG8_MMA(1, 1, At, B1); PG8_BAR; PG8_SCHED;
;     ...
; #pragma unroll
;         for (int a = 0; a < 2; ++a)
; #pragma unroll
;             for (int b = 0; b < 2; ++b)
; #pragma unroll
;                 for (int m = 0; m < 4; ++m)
; #pragma unroll
;                     for (int n = 0; n < 2; ++n) acc[a][b][m][n] = (f32x4){0.f, 0.f, 0.f, 0.f};
.LBB0_114:
	s_ashr_i32 s21, s20, 31
	s_lshl_b64 s[8:9], s[20:21], 20
	v_readlane_b32 s22, v254, 16
	v_readlane_b32 s23, v254, 17
	s_add_u32 s22, s22, s8
	s_addc_u32 s23, s23, s9
	s_and_b64 s[8:9], s[2:3], exec
	s_cselect_b32 s21, s23, s5
	s_cselect_b32 s26, s22, s4
	s_ashr_i32 s19, s18, 31
	s_lshl_b64 s[8:9], s[18:19], 20
	s_add_u32 s24, s30, s8
	s_addc_u32 s25, s31, s9
	s_and_b64 s[8:9], s[2:3], exec
	s_cselect_b32 s19, s25, s7
	s_cselect_b32 s27, s24, s6
	s_add_u32 s4, s4, 0x80080
	s_addc_u32 s5, s5, 0
	s_add_u32 s28, s6, 0x100
	s_addc_u32 s29, s7, 0
	s_mov_b32 s52, -2
	s_add_u32 s6, s4, 0xfff80080
	s_addc_u32 s7, s5, -1
	s_add_i32 s53, 0, 0x10000
	s_cmp_eq_u32 s52, 28
	s_cselect_b32 s9, s21, s7
	s_cselect_b32 s8, s26, s6
	s_cselect_b32 s7, s19, s29
	s_cselect_b32 s6, s27, s28
	s_add_i32 s56, 0, 0x14000
	v_add_u32_e32 v142, s53, v162
	v_add_u32_e32 v156, s56, v162
	ds_read_b128 v[130:133], v142
	ds_read_b128 v[134:137], v142 offset:1024
	ds_read_b128 v[138:141], v142 offset:2048
	ds_read_b128 v[142:145], v142 offset:3072
	ds_read_b128 v[178:181], v156
	ds_read_b128 v[182:185], v156 offset:1024
	ds_read_b128 v[200:203], v156 offset:2048
	ds_read_b128 v[204:207], v156 offset:3072
	s_add_i32 m0, s34, 0xc000
	ds_read_b128 v[208:211], v176
	ds_read_b128 v[212:215], v176 offset:1024
	ds_read_b128 v[216:219], v176 offset:2048
	ds_read_b128 v[220:223], v176 offset:3072
	ds_read_b128 v[224:227], v176 offset:4096
	ds_read_b128 v[228:231], v176 offset:5120
	ds_read_b128 v[232:235], v176 offset:6144
	ds_read_b128 v[236:239], v176 offset:7168
	global_load_lds_dwordx4 v152, s[4:5]
	s_add_i32 m0, s34, 0xe000
	s_nop 0
	global_load_lds_dwordx4 v154, s[4:5]
	s_waitcnt vmcnt(8)
	s_waitcnt lgkmcnt(0)
	s_barrier
	s_setprio 1
	s_waitcnt lgkmcnt(0)
	v_mfma_f32_16x16x32_bf16 v[126:129], v[130:133], v[208:211], 0
	v_mfma_f32_16x16x32_bf16 v[122:125], v[138:141], v[208:211], 0
	v_mfma_f32_16x16x32_bf16 v[118:121], v[130:133], v[216:219], 0
	v_mfma_f32_16x16x32_bf16 v[110:113], v[138:141], v[216:219], 0
	v_mfma_f32_16x16x32_bf16 v[102:105], v[130:133], v[224:227], 0
	v_mfma_f32_16x16x32_bf16 v[94:97], v[138:141], v[224:227], 0
	v_mfma_f32_16x16x32_bf16 v[86:89], v[130:133], v[232:235], 0
	v_mfma_f32_16x16x32_bf16 v[78:81], v[138:141], v[232:235], 0
	v_mfma_f32_16x16x32_bf16 v[126:129], v[134:137], v[212:215], v[126:129]
	v_mfma_f32_16x16x32_bf16 v[122:125], v[142:145], v[212:215], v[122:125]
	v_mfma_f32_16x16x32_bf16 v[118:121], v[134:137], v[220:223], v[118:121]
	v_mfma_f32_16x16x32_bf16 v[110:113], v[142:145], v[220:223], v[110:113]
	v_mfma_f32_16x16x32_bf16 v[102:105], v[134:137], v[228:231], v[102:105]
	v_mfma_f32_16x16x32_bf16 v[94:97], v[142:145], v[228:231], v[94:97]
	v_mfma_f32_16x16x32_bf16 v[86:89], v[134:137], v[236:239], v[86:89]
	v_mfma_f32_16x16x32_bf16 v[78:81], v[142:145], v[236:239], v[78:81]
	s_setprio 0
	s_setprio 1
	v_mfma_f32_16x16x32_bf16 v[114:117], v[178:181], v[208:211], 0
	v_mfma_f32_16x16x32_bf16 v[106:109], v[200:203], v[208:211], 0
	v_mfma_f32_16x16x32_bf16 v[98:101], v[178:181], v[216:219], 0
	v_mfma_f32_16x16x32_bf16 v[90:93], v[200:203], v[216:219], 0
	v_mfma_f32_16x16x32_bf16 v[82:85], v[178:181], v[224:227], 0
	v_mfma_f32_16x16x32_bf16 v[74:77], v[200:203], v[224:227], 0
	v_mfma_f32_16x16x32_bf16 v[70:73], v[178:181], v[232:235], 0
	v_mfma_f32_16x16x32_bf16 v[66:69], v[200:203], v[232:235], 0
	v_mfma_f32_16x16x32_bf16 v[114:117], v[182:185], v[212:215], v[114:117]
	v_mfma_f32_16x16x32_bf16 v[106:109], v[204:207], v[212:215], v[106:109]
	v_mfma_f32_16x16x32_bf16 v[98:101], v[182:185], v[220:223], v[98:101]
	v_mfma_f32_16x16x32_bf16 v[90:93], v[204:207], v[220:223], v[90:93]
	v_mfma_f32_16x16x32_bf16 v[82:85], v[182:185], v[228:231], v[82:85]
	v_mfma_f32_16x16x32_bf16 v[74:77], v[204:207], v[228:231], v[74:77]
	v_mfma_f32_16x16x32_bf16 v[70:73], v[182:185], v[236:239], v[70:73]
	v_mfma_f32_16x16x32_bf16 v[66:69], v[204:207], v[236:239], v[66:69]
	s_setprio 0
	s_barrier
	s_add_i32 s53, s53, s33
	s_add_u32 s84, s6, s44
	s_addc_u32 s85, s7, s45
	s_mov_b32 m0, s53
	ds_read_b128 v[208:211], v176 offset:16384
	ds_read_b128 v[212:215], v176 offset:17408
	ds_read_b128 v[216:219], v176 offset:18432
	ds_read_b128 v[220:223], v176 offset:19456
	ds_read_b128 v[224:227], v176 offset:20480
	ds_read_b128 v[228:231], v176 offset:21504
	ds_read_b128 v[232:235], v176 offset:22528
	ds_read_b128 v[236:239], v176 offset:23552
	global_load_lds_dwordx4 v0, s[6:7]
	s_add_i32 m0, s53, 0x2000
	s_add_u32 s54, s6, 0x80000
	s_addc_u32 s55, s7, 0
	s_add_i32 s53, s56, s33
	global_load_lds_dwordx4 v146, s[6:7]
	s_mov_b32 m0, s53
	s_nop 0
	global_load_lds_dwordx4 v0, s[54:55]
	s_add_i32 m0, s53, 0x2000
	s_nop 0
	global_load_lds_dwordx4 v146, s[54:55]
	s_add_u32 s86, s8, s44
	s_addc_u32 s87, s9, s45
	s_mov_b32 m0, s34
	s_nop 0
	global_load_lds_dwordx4 v150, s[8:9]
	s_mov_b32 m0, s35
	s_nop 0
	global_load_lds_dwordx4 v148, s[8:9]
	s_waitcnt vmcnt(8)
	s_waitcnt lgkmcnt(0)
	s_barrier
; #define PG8_STAGE(bufoff, gbase, voff) do { _Pragma("unroll") for (int _i = 0; _i < 2; ++_i) \
;         __builtin_amdgcn_global_load_lds((const unsigned*)((const char*)(gbase) + (voff)[_i]), (PG8_LAS unsigned*)(lds + (bufoff) + ldsw + _i * 8192), 16, 0, 0); } while (0)
; #define PG8_LDA(dst, b, h) do { _Pragma("unroll") for (int m = 0; m < 4; ++m) _Pragma("unroll") for (int k = 0; k < 2; ++k) dst[m][k] = *(const PG8_LAS bf16x8*)(lds + PG8_SA(b, h) + aoff + m * 2048 + k * 1024); } while (0)
; #define PG8_LDB(dst, b, h) do { _Pragma("unroll") for (int n = 0; n < 2; ++n) _Pragma("unroll") for (int k = 0; k < 2; ++k) dst[n][k] = *(const PG8_LAS bf16x8*)(lds + PG8_SB(b, h) + boff + n * 2048 + k * 1024); } while (0)
; template <class Epi, class Sched, bool ALIGN_EPI = false, bool SP2 = false>
; __device__ __forceinline__ void gemm_phase(PG8_LAS unsigned char* lds, const Gemm g, const Sched& S, const Epi& E) {
;     ...
;         for (int t = 0; t < nt; t += 2) {
;             const bool last = (t == nt - 2);
;             const char* a1 = cA + (size_t)(t + 1) * kstep;
;             const char* a2 = last ? nA : cA + (size_t)(t + 2) * kstep; const char* b2 = last ? nB : cB + (size_t)(t + 2) * kstep;
;             const char* a3 = a2 + kstep; const char* b3 = b2 + kstep;
;             if (last && has_next) S.a_ready(nxt);
;             if constexpr (SP2) {
;             PG8_LDB(B0, 0, 0); PG8_LDB(B1, 0, 1); PG8_SCHED; PG8_LDA(At, 0, 0); PG8_STAGE(PG8_SA(1, 1), a1 + hstep, voffA);
;             PG8_WAIT_V(8); PG8_WAIT_L(0); PG8_BAR; PG8_MMA(0, 0, At, B0); PG8_MMA(0, 1, At, B1); PG8_BAR; PG8_SCHED;
;             PG8_LDA(At, 0, 1); PG8_STAGE(PG8_SB(0, 0), b2, voffB); PG8_STAGE(PG8_SB(0, 1), b2 + hstep, voffB); PG8_STAGE(PG8_SA(0, 0), a2, voffA);
;             PG8_WAIT_V(8); PG8_WAIT_L(0); PG8_BAR; PG8_MMA(1, 0, At, B0); PG8_MMA(1, 1, At, B1); PG8_BAR; PG8_SCHED;
;             PG8_LDB(B0, 1, 0); PG8_LDB(B1, 1, 1); PG8_SCHED; PG8_LDA(At, 1, 0); PG8_STAGE(PG8_SA(0, 1), a2 + hstep, voffA);
;             PG8_WAIT_V(8); PG8_WAIT_L(0); PG8_BAR; PG8_MMA(0, 0, At, B0); PG8_MMA(0, 1, At, B1); PG8_BAR; PG8_SCHED;
;             PG8_LDA(At, 1, 1); PG8_STAGE(PG8_SB(1, 0), b3, voffB); PG8_STAGE(PG8_SB(1, 1), b3 + hstep, voffB); PG8_STAGE(PG8_SA(1, 0), a3, voffA);
;             PG8_WAIT_V(8); PG8_WAIT_L(0); PG8_BAR; PG8_MMA(1, 0, At, B0); PG8_MMA(1, 1, At, B1); PG8_BAR; PG8_SCHED;
	s_setprio 1
	s_waitcnt lgkmcnt(0)
	v_mfma_f32_16x16x32_bf16 v[62:65], v[130:133], v[208:211], 0
	v_mfma_f32_16x16x32_bf16 v[58:61], v[138:141], v[208:211], 0
	v_mfma_f32_16x16x32_bf16 v[54:57], v[130:133], v[216:219], 0
	v_mfma_f32_16x16x32_bf16 v[46:49], v[138:141], v[216:219], 0
	v_mfma_f32_16x16x32_bf16 v[38:41], v[130:133], v[224:227], 0
	v_mfma_f32_16x16x32_bf16 v[30:33], v[138:141], v[224:227], 0
	v_mfma_f32_16x16x32_bf16 v[22:25], v[130:133], v[232:235], 0
	v_mfma_f32_16x16x32_bf16 v[14:17], v[138:141], v[232:235], 0
	v_mfma_f32_16x16x32_bf16 v[62:65], v[134:137], v[212:215], v[62:65]
	v_mfma_f32_16x16x32_bf16 v[58:61], v[142:145], v[212:215], v[58:61]
	v_mfma_f32_16x16x32_bf16 v[54:57], v[134:137], v[220:223], v[54:57]
	v_mfma_f32_16x16x32_bf16 v[46:49], v[142:145], v[220:223], v[46:49]
	v_mfma_f32_16x16x32_bf16 v[38:41], v[134:137], v[228:231], v[38:41]
	v_mfma_f32_16x16x32_bf16 v[30:33], v[142:145], v[228:231], v[30:33]
	v_mfma_f32_16x16x32_bf16 v[22:25], v[134:137], v[236:239], v[22:25]
	v_mfma_f32_16x16x32_bf16 v[14:17], v[142:145], v[236:239], v[14:17]
	s_setprio 0
	s_setprio 1
	v_mfma_f32_16x16x32_bf16 v[50:53], v[178:181], v[208:211], 0
	v_mfma_f32_16x16x32_bf16 v[42:45], v[200:203], v[208:211], 0
	v_mfma_f32_16x16x32_bf16 v[34:37], v[178:181], v[216:219], 0
	v_mfma_f32_16x16x32_bf16 v[26:29], v[200:203], v[216:219], 0
	v_mfma_f32_16x16x32_bf16 v[18:21], v[178:181], v[224:227], 0
	v_mfma_f32_16x16x32_bf16 v[10:13], v[200:203], v[224:227], 0
	v_mfma_f32_16x16x32_bf16 v[6:9], v[178:181], v[232:235], 0
	v_mfma_f32_16x16x32_bf16 v[2:5], v[200:203], v[232:235], 0
	v_mfma_f32_16x16x32_bf16 v[50:53], v[182:185], v[212:215], v[50:53]
	v_mfma_f32_16x16x32_bf16 v[42:45], v[204:207], v[212:215], v[42:45]
	v_mfma_f32_16x16x32_bf16 v[34:37], v[182:185], v[220:223], v[34:37]
	v_mfma_f32_16x16x32_bf16 v[26:29], v[204:207], v[220:223], v[26:29]
	v_mfma_f32_16x16x32_bf16 v[18:21], v[182:185], v[228:231], v[18:21]
	v_mfma_f32_16x16x32_bf16 v[10:13], v[204:207], v[228:231], v[10:13]
	v_mfma_f32_16x16x32_bf16 v[6:9], v[182:185], v[236:239], v[6:9]
	v_mfma_f32_16x16x32_bf16 v[2:5], v[204:207], v[236:239], v[2:5]
	s_setprio 0
	s_barrier
	s_add_i32 s53, 0, 0x18000
	s_add_i32 s54, 0, 0x1c000
	v_add_u32_e32 v142, s53, v162
	v_add_u32_e32 v158, s54, v162
	ds_read_b128 v[130:133], v142
	ds_read_b128 v[134:137], v142 offset:1024
	ds_read_b128 v[138:141], v142 offset:2048
	ds_read_b128 v[142:145], v142 offset:3072
	ds_read_b128 v[178:181], v158
	ds_read_b128 v[182:185], v158 offset:1024
	ds_read_b128 v[200:203], v158 offset:2048
	ds_read_b128 v[204:207], v158 offset:3072
	s_add_u32 s8, s8, 0x80000
	s_addc_u32 s9, s9, 0
	s_mov_b32 m0, s36
	ds_read_b128 v[208:211], v176 offset:32768
	ds_read_b128 v[212:215], v176 offset:33792
	ds_read_b128 v[216:219], v176 offset:34816
	ds_read_b128 v[220:223], v176 offset:35840
	ds_read_b128 v[224:227], v176 offset:36864
	ds_read_b128 v[228:231], v176 offset:37888
	ds_read_b128 v[232:235], v176 offset:38912
	ds_read_b128 v[236:239], v176 offset:39936
	global_load_lds_dwordx4 v150, s[8:9]
	s_mov_b32 m0, s37
	s_nop 0
	global_load_lds_dwordx4 v148, s[8:9]
	s_waitcnt vmcnt(8)
	s_waitcnt lgkmcnt(0)
	s_barrier
	s_setprio 1
	s_waitcnt lgkmcnt(0)
	v_mfma_f32_16x16x32_bf16 v[126:129], v[130:133], v[208:211], v[126:129]
	v_mfma_f32_16x16x32_bf16 v[122:125], v[138:141], v[208:211], v[122:125]
	v_mfma_f32_16x16x32_bf16 v[118:121], v[130:133], v[216:219], v[118:121]
	v_mfma_f32_16x16x32_bf16 v[110:113], v[138:141], v[216:219], v[110:113]
	v_mfma_f32_16x16x32_bf16 v[102:105], v[130:133], v[224:227], v[102:105]
	v_mfma_f32_16x16x32_bf16 v[94:97], v[138:141], v[224:227], v[94:97]
	v_mfma_f32_16x16x32_bf16 v[86:89], v[130:133], v[232:235], v[86:89]
	v_mfma_f32_16x16x32_bf16 v[78:81], v[138:141], v[232:235], v[78:81]
	v_mfma_f32_16x16x32_bf16 v[126:129], v[134:137], v[212:215], v[126:129]
	v_mfma_f32_16x16x32_bf16 v[122:125], v[142:145], v[212:215], v[122:125]
	v_mfma_f32_16x16x32_bf16 v[118:121], v[134:137], v[220:223], v[118:121]
	v_mfma_f32_16x16x32_bf16 v[110:113], v[142:145], v[220:223], v[110:113]
	v_mfma_f32_16x16x32_bf16 v[102:105], v[134:137], v[228:231], v[102:105]
	v_mfma_f32_16x16x32_bf16 v[94:97], v[142:145], v[228:231], v[94:97]
	v_mfma_f32_16x16x32_bf16 v[86:89], v[134:137], v[236:239], v[86:89]
	v_mfma_f32_16x16x32_bf16 v[78:81], v[142:145], v[236:239], v[78:81]
	s_setprio 0
	s_setprio 1
	v_mfma_f32_16x16x32_bf16 v[114:117], v[178:181], v[208:211], v[114:117]
	v_mfma_f32_16x16x32_bf16 v[106:109], v[200:203], v[208:211], v[106:109]
	v_mfma_f32_16x16x32_bf16 v[98:101], v[178:181], v[216:219], v[98:101]
	v_mfma_f32_16x16x32_bf16 v[90:93], v[200:203], v[216:219], v[90:93]
	v_mfma_f32_16x16x32_bf16 v[82:85], v[178:181], v[224:227], v[82:85]
	v_mfma_f32_16x16x32_bf16 v[74:77], v[200:203], v[224:227], v[74:77]
	v_mfma_f32_16x16x32_bf16 v[70:73], v[178:181], v[232:235], v[70:73]
	v_mfma_f32_16x16x32_bf16 v[66:69], v[200:203], v[232:235], v[66:69]
	v_mfma_f32_16x16x32_bf16 v[114:117], v[182:185], v[212:215], v[114:117]
	v_mfma_f32_16x16x32_bf16 v[106:109], v[204:207], v[212:215], v[106:109]
	v_mfma_f32_16x16x32_bf16 v[98:101], v[182:185], v[220:223], v[98:101]
	v_mfma_f32_16x16x32_bf16 v[90:93], v[204:207], v[220:223], v[90:93]
	v_mfma_f32_16x16x32_bf16 v[82:85], v[182:185], v[228:231], v[82:85]
	v_mfma_f32_16x16x32_bf16 v[74:77], v[204:207], v[228:231], v[74:77]
	v_mfma_f32_16x16x32_bf16 v[70:73], v[182:185], v[236:239], v[70:73]
	v_mfma_f32_16x16x32_bf16 v[66:69], v[204:207], v[236:239], v[66:69]
	s_setprio 0
	s_barrier
; #define PG8_STAGE(bufoff, gbase, voff) do { _Pragma("unroll") for (int _i = 0; _i < 2; ++_i) \
;         __builtin_amdgcn_global_load_lds((const unsigned*)((const char*)(gbase) + (voff)[_i]), (PG8_LAS unsigned*)(lds + (bufoff) + ldsw + _i * 8192), 16, 0, 0); } while (0)
; #define PG8_LDA(dst, b, h) do { _Pragma("unroll") for (int m = 0; m < 4; ++m) _Pragma("unroll") for (int k = 0; k < 2; ++k) dst[m][k] = *(const PG8_LAS bf16x8*)(lds + PG8_SA(b, h) + aoff + m * 2048 + k * 1024); } while (0)
; #define PG8_LDB(dst, b, h) do { _Pragma("unroll") for (int n = 0; n < 2; ++n) _Pragma("unroll") for (int k = 0; k < 2; ++k) dst[n][k] = *(const PG8_LAS bf16x8*)(lds + PG8_SB(b, h) + boff + n * 2048 + k * 1024); } while (0)
; template <class Epi, class Sched, bool ALIGN_EPI = false, bool SP2 = false>
; __device__ __forceinline__ void gemm_phase(PG8_LAS unsigned char* lds, const Gemm g, const Sched& S, const Epi& E) {
;     ...
;         for (int t = 0; t < nt; t += 2) {
;             const bool last = (t == nt - 2);
;             const char* a1 = cA + (size_t)(t + 1) * kstep;
;             const char* a2 = last ? nA : cA + (size_t)(t + 2) * kstep; const char* b2 = last ? nB : cB + (size_t)(t + 2) * kstep;
;             const char* a3 = a2 + kstep; const char* b3 = b2 + kstep;
;             if (last && has_next) S.a_ready(nxt);
;             if constexpr (SP2) {
;             PG8_LDB(B0, 0, 0); PG8_LDB(B1, 0, 1); PG8_SCHED; PG8_LDA(At, 0, 0); PG8_STAGE(PG8_SA(1, 1), a1 + hstep, voffA);
;             PG8_WAIT_V(8); PG8_WAIT_L(0); PG8_BAR; PG8_MMA(0, 0, At, B0); PG8_MMA(0, 1, At, B1); PG8_BAR; PG8_SCHED;
;             PG8_LDA(At, 0, 1); PG8_STAGE(PG8_SB(0, 0), b2, voffB); PG8_STAGE(PG8_SB(0, 1), b2 + hstep, voffB); PG8_STAGE(PG8_SA(0, 0), a2, voffA);
;             PG8_WAIT_V(8); PG8_WAIT_L(0); PG8_BAR; PG8_MMA(1, 0, At, B0); PG8_MMA(1, 1, At, B1); PG8_BAR; PG8_SCHED;
;             PG8_LDB(B0, 1, 0); PG8_LDB(B1, 1, 1); PG8_SCHED; PG8_LDA(At, 1, 0); PG8_STAGE(PG8_SA(0, 1), a2 + hstep, voffA);
;             PG8_WAIT_V(8); PG8_WAIT_L(0); PG8_BAR; PG8_MMA(0, 0, At, B0); PG8_MMA(0, 1, At, B1); PG8_BAR; PG8_SCHED;
;             PG8_LDA(At, 1, 1); PG8_STAGE(PG8_SB(1, 0), b3, voffB); PG8_STAGE(PG8_SB(1, 1), b3 + hstep, voffB); PG8_STAGE(PG8_SA(1, 0), a3, voffA);
;             PG8_WAIT_V(8); PG8_WAIT_L(0); PG8_BAR; PG8_MMA(1, 0, At, B0); PG8_MMA(1, 1, At, B1); PG8_BAR; PG8_SCHED;
	s_add_i32 s8, s53, s33
	s_mov_b32 m0, s8
	ds_read_b128 v[208:211], v176 offset:49152
	ds_read_b128 v[212:215], v176 offset:50176
	ds_read_b128 v[216:219], v176 offset:51200
	ds_read_b128 v[220:223], v176 offset:52224
	ds_read_b128 v[224:227], v176 offset:53248
	ds_read_b128 v[228:231], v176 offset:54272
	ds_read_b128 v[232:235], v176 offset:55296
	ds_read_b128 v[236:239], v176 offset:56320
	global_load_lds_dwordx4 v0, s[84:85]
	s_add_i32 m0, s8, 0x2000
	s_add_u32 s6, s6, 0x80080
	s_addc_u32 s7, s7, 0
	s_add_i32 s8, s54, s33
	global_load_lds_dwordx4 v146, s[84:85]
	s_mov_b32 m0, s8
	s_nop 0
	global_load_lds_dwordx4 v0, s[6:7]
	s_add_i32 m0, s8, 0x2000
	s_nop 0
	global_load_lds_dwordx4 v146, s[6:7]
	s_mov_b32 m0, s41
	s_nop 0
	global_load_lds_dwordx4 v150, s[86:87]
	s_mov_b32 m0, s42
	s_nop 0
	global_load_lds_dwordx4 v148, s[86:87]
	s_waitcnt vmcnt(8)
	s_waitcnt lgkmcnt(0)
	s_barrier
	s_setprio 1
	s_waitcnt lgkmcnt(0)
	v_mfma_f32_16x16x32_bf16 v[62:65], v[130:133], v[208:211], v[62:65]
	v_mfma_f32_16x16x32_bf16 v[58:61], v[138:141], v[208:211], v[58:61]
	v_mfma_f32_16x16x32_bf16 v[54:57], v[130:133], v[216:219], v[54:57]
	v_mfma_f32_16x16x32_bf16 v[46:49], v[138:141], v[216:219], v[46:49]
	v_mfma_f32_16x16x32_bf16 v[38:41], v[130:133], v[224:227], v[38:41]
	v_mfma_f32_16x16x32_bf16 v[30:33], v[138:141], v[224:227], v[30:33]
	v_mfma_f32_16x16x32_bf16 v[22:25], v[130:133], v[232:235], v[22:25]
	v_mfma_f32_16x16x32_bf16 v[14:17], v[138:141], v[232:235], v[14:17]
	v_mfma_f32_16x16x32_bf16 v[62:65], v[134:137], v[212:215], v[62:65]
	v_mfma_f32_16x16x32_bf16 v[58:61], v[142:145], v[212:215], v[58:61]
	v_mfma_f32_16x16x32_bf16 v[54:57], v[134:137], v[220:223], v[54:57]
	v_mfma_f32_16x16x32_bf16 v[46:49], v[142:145], v[220:223], v[46:49]
	v_mfma_f32_16x16x32_bf16 v[38:41], v[134:137], v[228:231], v[38:41]
	v_mfma_f32_16x16x32_bf16 v[30:33], v[142:145], v[228:231], v[30:33]
	v_mfma_f32_16x16x32_bf16 v[22:25], v[134:137], v[236:239], v[22:25]
	v_mfma_f32_16x16x32_bf16 v[14:17], v[142:145], v[236:239], v[14:17]
	s_setprio 0
	s_setprio 1
	v_mfma_f32_16x16x32_bf16 v[50:53], v[178:181], v[208:211], v[50:53]
	v_mfma_f32_16x16x32_bf16 v[42:45], v[200:203], v[208:211], v[42:45]
	v_mfma_f32_16x16x32_bf16 v[34:37], v[178:181], v[216:219], v[34:37]
	v_mfma_f32_16x16x32_bf16 v[26:29], v[200:203], v[216:219], v[26:29]
	v_mfma_f32_16x16x32_bf16 v[18:21], v[178:181], v[224:227], v[18:21]
	v_mfma_f32_16x16x32_bf16 v[10:13], v[200:203], v[224:227], v[10:13]
	v_mfma_f32_16x16x32_bf16 v[6:9], v[178:181], v[232:235], v[6:9]
	v_mfma_f32_16x16x32_bf16 v[2:5], v[200:203], v[232:235], v[2:5]
	v_mfma_f32_16x16x32_bf16 v[50:53], v[182:185], v[212:215], v[50:53]
	v_mfma_f32_16x16x32_bf16 v[42:45], v[204:207], v[212:215], v[42:45]
	v_mfma_f32_16x16x32_bf16 v[34:37], v[182:185], v[220:223], v[34:37]
	v_mfma_f32_16x16x32_bf16 v[26:29], v[204:207], v[220:223], v[26:29]
	v_mfma_f32_16x16x32_bf16 v[18:21], v[182:185], v[228:231], v[18:21]
	v_mfma_f32_16x16x32_bf16 v[10:13], v[204:207], v[228:231], v[10:13]
	v_mfma_f32_16x16x32_bf16 v[6:9], v[182:185], v[236:239], v[6:9]
	v_mfma_f32_16x16x32_bf16 v[2:5], v[204:207], v[236:239], v[2:5]
	s_setprio 0
	s_barrier
	s_add_i32 s52, s52, 2
	s_add_u32 s4, s4, 0x100
	s_addc_u32 s5, s5, 0
	s_add_u32 s28, s28, 0x100
	s_addc_u32 s29, s29, 0
	s_cmp_gt_u32 s52, 29

;     __device__ bool next(int i, Unit& u) const { const int j = first + i * G; if (j >= count) return false; u.pm = j / nN; u.pn = j % nN; return true; }
; #define PG8_BAR __builtin_amdgcn_s_barrier()
; template <class Epi, class Sched, bool ALIGN_EPI = false, bool SP2 = false>
; __device__ __forceinline__ void gemm_phase(PG8_LAS unsigned char* lds, const Gemm g, const Sched& S, const Epi& E) {
;     ...
;     for (;;) {
;         const bool has_next = S.next(ui + 1, nxt);
;         const char* nA = has_next ? (const char*)g.A + (size_t)nxt.pm * tstep : cA; const char* nB = has_next ? (const char*)g.Bt + (size_t)nxt.pn * tstep : cB;
;         for (int t = 0; t < nt; t += 2) {
;             const bool last = (t == nt - 2);
;             const char* a1 = cA + (size_t)(t + 1) * kstep;
;             const char* a2 = last ? nA : cA + (size_t)(t + 2) * kstep; const char* b2 = last ? nB : cB + (size_t)(t + 2) * kstep;
;             const char* a3 = a2 + kstep; const char* b3 = b2 + kstep;
;             if (last && has_next) S.a_ready(nxt);
;             if constexpr (SP2) {
;             PG8_LDB(B0, 0, 0); PG8_LDB(B1, 0, 1); PG8_SCHED; PG8_LDA(At, 0, 0); PG8_STAGE(PG8_SA(1, 1), a1 + hstep, voffA);
;             PG8_WAIT_V(8); PG8_WAIT_L(0); PG8_BAR; PG8_MMA(0, 0, At, B0); PG8_MMA(0, 1, At, B1); PG8_BAR; PG8_SCHED;
;             PG8_LDA(At, 0, 1); PG8_STAGE(PG8_SB(0, 0), b2, voffB); PG8_STAGE(PG8_SB(0, 1), b2 + hstep, voffB); PG8_STAGE(PG8_SA(0, 0), a2, voffA);
;             PG8_WAIT_V(8); PG8_WAIT_L(0); PG8_BAR; PG8_MMA(1, 0, At, B0); PG8_MMA(1, 1, At, B1); PG8_BAR; PG8_SCHED;
;             PG8_LDB(B0, 1, 0); PG8_LDB(B1, 1, 1); PG8_SCHED; PG8_LDA(At, 1, 0); PG8_STAGE(PG8_SA(0, 1), a2 + hstep, voffA);
;             PG8_WAIT_V(8); PG8_WAIT_L(0); PG8_BAR; PG8_MMA(0, 0, At, B0); PG8_MMA(0, 1, At, B1); PG8_BAR; PG8_SCHED;
;             PG8_LDA(At, 1, 1); PG8_STAGE(PG8_SB(1, 0), b3, voffB); PG8_STAGE(PG8_SB(1, 1), b3 + hstep, voffB); PG8_STAGE(PG8_SA(1, 0), a3, voffA);
;             PG8_WAIT_V(8); PG8_WAIT_L(0); PG8_BAR; PG8_MMA(1, 0, At, B0); PG8_MMA(1, 1, At, B1); PG8_BAR; PG8_SCHED;
;     ...
; #pragma unroll
;         for (int a = 0; a < 2; ++a)
; #pragma unroll
;             for (int b = 0; b < 2; ++b)
; #pragma unroll
;                 for (int m = 0; m < 4; ++m)
; #pragma unroll
;                     for (int n = 0; n < 2; ++n) acc[a][b][m][n] = (f32x4){0.f, 0.f, 0.f, 0.f};
.LBB0_965:
	s_ashr_i32 s9, s8, 31
	s_lshl_b64 s[10:11], s[8:9], 20
	v_readlane_b32 s12, v254, 16
	v_readlane_b32 s13, v254, 17
	s_add_u32 s10, s12, s10
	s_addc_u32 s11, s13, s11
	s_and_b64 s[12:13], s[0:1], exec
	s_cselect_b32 s9, s11, s15
	s_cselect_b32 s33, s10, s14
	s_ashr_i32 s7, s6, 31
	s_lshl_b64 s[12:13], s[6:7], 20
	s_add_u32 s12, s20, s12
	s_addc_u32 s13, s21, s13
	s_and_b64 s[18:19], s[0:1], exec
	s_cselect_b32 s7, s13, s17
	s_cselect_b32 s34, s12, s16
	s_add_u32 s14, s14, 0x80080
	s_addc_u32 s15, s15, 0
	s_add_u32 s35, s16, 0x100
	s_addc_u32 s36, s17, 0
	s_mov_b32 s37, -2
	s_add_u32 s16, s14, 0xfff80080
	s_addc_u32 s17, s15, -1
	s_add_i32 s40, 0, 0x10000
	s_cmp_eq_u32 s37, 28
	s_cselect_b32 s19, s9, s17
	s_cselect_b32 s18, s33, s16
	s_cselect_b32 s17, s7, s36
	s_cselect_b32 s16, s34, s35
	s_add_i32 s42, 0, 0x14000
	v_add_u32_e32 v156, s40, v145
	v_add_u32_e32 v160, s42, v145
	ds_read_b128 v[140:143], v156
	ds_read_b128 v[148:151], v156 offset:1024
	ds_read_b128 v[152:155], v156 offset:2048
	ds_read_b128 v[156:159], v156 offset:3072
	ds_read_b128 v[164:167], v160
	ds_read_b128 v[172:175], v160 offset:1024
	ds_read_b128 v[176:179], v160 offset:2048
	ds_read_b128 v[180:183], v160 offset:3072
	s_add_i32 m0, s23, 0xc000
	ds_read_b128 v[200:203], v147
	ds_read_b128 v[204:207], v147 offset:1024
	ds_read_b128 v[208:211], v147 offset:2048
	ds_read_b128 v[212:215], v147 offset:3072
	ds_read_b128 v[216:219], v147 offset:4096
	ds_read_b128 v[220:223], v147 offset:5120
	ds_read_b128 v[224:227], v147 offset:6144
	ds_read_b128 v[228:231], v147 offset:7168
	global_load_lds_dwordx4 v136, s[14:15]
	s_add_i32 m0, s23, 0xe000
	s_nop 0
	global_load_lds_dwordx4 v138, s[14:15]
	s_waitcnt vmcnt(8)
	s_waitcnt lgkmcnt(0)
	s_barrier
	s_setprio 1
	s_waitcnt lgkmcnt(0)
	v_mfma_f32_16x16x32_bf16 v[126:129], v[140:143], v[200:203], 0
	v_mfma_f32_16x16x32_bf16 v[118:121], v[152:155], v[200:203], 0
	v_mfma_f32_16x16x32_bf16 v[110:113], v[140:143], v[208:211], 0
	v_mfma_f32_16x16x32_bf16 v[102:105], v[152:155], v[208:211], 0
	v_mfma_f32_16x16x32_bf16 v[94:97], v[140:143], v[216:219], 0
	v_mfma_f32_16x16x32_bf16 v[86:89], v[152:155], v[216:219], 0
	v_mfma_f32_16x16x32_bf16 v[78:81], v[140:143], v[224:227], 0
	v_mfma_f32_16x16x32_bf16 v[70:73], v[152:155], v[224:227], 0
	v_mfma_f32_16x16x32_bf16 v[126:129], v[148:151], v[204:207], v[126:129]
	v_mfma_f32_16x16x32_bf16 v[118:121], v[156:159], v[204:207], v[118:121]
	v_mfma_f32_16x16x32_bf16 v[110:113], v[148:151], v[212:215], v[110:113]
	v_mfma_f32_16x16x32_bf16 v[102:105], v[156:159], v[212:215], v[102:105]
	v_mfma_f32_16x16x32_bf16 v[94:97], v[148:151], v[220:223], v[94:97]
	v_mfma_f32_16x16x32_bf16 v[86:89], v[156:159], v[220:223], v[86:89]
	v_mfma_f32_16x16x32_bf16 v[78:81], v[148:151], v[228:231], v[78:81]
	v_mfma_f32_16x16x32_bf16 v[70:73], v[156:159], v[228:231], v[70:73]
	s_setprio 0
	s_setprio 1
	v_mfma_f32_16x16x32_bf16 v[122:125], v[164:167], v[200:203], 0
	v_mfma_f32_16x16x32_bf16 v[114:117], v[176:179], v[200:203], 0
	v_mfma_f32_16x16x32_bf16 v[106:109], v[164:167], v[208:211], 0
	v_mfma_f32_16x16x32_bf16 v[98:101], v[176:179], v[208:211], 0
	v_mfma_f32_16x16x32_bf16 v[90:93], v[164:167], v[216:219], 0
	v_mfma_f32_16x16x32_bf16 v[82:85], v[176:179], v[216:219], 0
	v_mfma_f32_16x16x32_bf16 v[74:77], v[164:167], v[224:227], 0
	v_mfma_f32_16x16x32_bf16 v[66:69], v[176:179], v[224:227], 0
	v_mfma_f32_16x16x32_bf16 v[122:125], v[172:175], v[204:207], v[122:125]
	v_mfma_f32_16x16x32_bf16 v[114:117], v[180:183], v[204:207], v[114:117]
	v_mfma_f32_16x16x32_bf16 v[106:109], v[172:175], v[212:215], v[106:109]
	v_mfma_f32_16x16x32_bf16 v[98:101], v[180:183], v[212:215], v[98:101]
	v_mfma_f32_16x16x32_bf16 v[90:93], v[172:175], v[220:223], v[90:93]
	v_mfma_f32_16x16x32_bf16 v[82:85], v[180:183], v[220:223], v[82:85]
	v_mfma_f32_16x16x32_bf16 v[74:77], v[172:175], v[228:231], v[74:77]
	v_mfma_f32_16x16x32_bf16 v[66:69], v[180:183], v[228:231], v[66:69]
	s_setprio 0
	s_barrier
	s_add_i32 s40, s40, s22
	s_add_u32 s48, s16, s44
	s_addc_u32 s49, s17, s45
	s_mov_b32 m0, s40
	ds_read_b128 v[200:203], v147 offset:16384
	ds_read_b128 v[204:207], v147 offset:17408
	ds_read_b128 v[208:211], v147 offset:18432
	ds_read_b128 v[212:215], v147 offset:19456
	ds_read_b128 v[216:219], v147 offset:20480
	ds_read_b128 v[220:223], v147 offset:21504
	ds_read_b128 v[224:227], v147 offset:22528
	ds_read_b128 v[228:231], v147 offset:23552
	global_load_lds_dwordx4 v0, s[16:17]
	s_add_i32 m0, s40, 0x2000
	s_add_u32 s40, s16, 0x80000
	s_addc_u32 s41, s17, 0
	s_add_i32 s42, s42, s22
	global_load_lds_dwordx4 v130, s[16:17]
	s_mov_b32 m0, s42
	s_nop 0
	global_load_lds_dwordx4 v0, s[40:41]
	s_add_i32 m0, s42, 0x2000
	s_nop 0
	global_load_lds_dwordx4 v130, s[40:41]
	s_add_u32 s50, s18, s44
	s_addc_u32 s51, s19, s45
	s_mov_b32 m0, s23
	s_nop 0
	global_load_lds_dwordx4 v134, s[18:19]
	s_mov_b32 m0, s24
	s_nop 0
	global_load_lds_dwordx4 v132, s[18:19]
	s_waitcnt vmcnt(8)
	s_waitcnt lgkmcnt(0)
	s_barrier
; #define PG8_STAGE(bufoff, gbase, voff) do { _Pragma("unroll") for (int _i = 0; _i < 2; ++_i) \
;         __builtin_amdgcn_global_load_lds((const unsigned*)((const char*)(gbase) + (voff)[_i]), (PG8_LAS unsigned*)(lds + (bufoff) + ldsw + _i * 8192), 16, 0, 0); } while (0)
; #define PG8_LDA(dst, b, h) do { _Pragma("unroll") for (int m = 0; m < 4; ++m) _Pragma("unroll") for (int k = 0; k < 2; ++k) dst[m][k] = *(const PG8_LAS bf16x8*)(lds + PG8_SA(b, h) + aoff + m * 2048 + k * 1024); } while (0)
; #define PG8_LDB(dst, b, h) do { _Pragma("unroll") for (int n = 0; n < 2; ++n) _Pragma("unroll") for (int k = 0; k < 2; ++k) dst[n][k] = *(const PG8_LAS bf16x8*)(lds + PG8_SB(b, h) + boff + n * 2048 + k * 1024); } while (0)
; template <class Epi, class Sched, bool ALIGN_EPI = false, bool SP2 = false>
; __device__ __forceinline__ void gemm_phase(PG8_LAS unsigned char* lds, const Gemm g, const Sched& S, const Epi& E) {
;     ...
;         for (int t = 0; t < nt; t += 2) {
;             const bool last = (t == nt - 2);
;             const char* a1 = cA + (size_t)(t + 1) * kstep;
;             const char* a2 = last ? nA : cA + (size_t)(t + 2) * kstep; const char* b2 = last ? nB : cB + (size_t)(t + 2) * kstep;
;             const char* a3 = a2 + kstep; const char* b3 = b2 + kstep;
;             if (last && has_next) S.a_ready(nxt);
;             if constexpr (SP2) {
;             PG8_LDB(B0, 0, 0); PG8_LDB(B1, 0, 1); PG8_SCHED; PG8_LDA(At, 0, 0); PG8_STAGE(PG8_SA(1, 1), a1 + hstep, voffA);
;             PG8_WAIT_V(8); PG8_WAIT_L(0); PG8_BAR; PG8_MMA(0, 0, At, B0); PG8_MMA(0, 1, At, B1); PG8_BAR; PG8_SCHED;
;             PG8_LDA(At, 0, 1); PG8_STAGE(PG8_SB(0, 0), b2, voffB); PG8_STAGE(PG8_SB(0, 1), b2 + hstep, voffB); PG8_STAGE(PG8_SA(0, 0), a2, voffA);
;             PG8_WAIT_V(8); PG8_WAIT_L(0); PG8_BAR; PG8_MMA(1, 0, At, B0); PG8_MMA(1, 1, At, B1); PG8_BAR; PG8_SCHED;
;             PG8_LDB(B0, 1, 0); PG8_LDB(B1, 1, 1); PG8_SCHED; PG8_LDA(At, 1, 0); PG8_STAGE(PG8_SA(0, 1), a2 + hstep, voffA);
;             PG8_WAIT_V(8); PG8_WAIT_L(0); PG8_BAR; PG8_MMA(0, 0, At, B0); PG8_MMA(0, 1, At, B1); PG8_BAR; PG8_SCHED;
;             PG8_LDA(At, 1, 1); PG8_STAGE(PG8_SB(1, 0), b3, voffB); PG8_STAGE(PG8_SB(1, 1), b3 + hstep, voffB); PG8_STAGE(PG8_SA(1, 0), a3, voffA);
;             PG8_WAIT_V(8); PG8_WAIT_L(0); PG8_BAR; PG8_MMA(1, 0, At, B0); PG8_MMA(1, 1, At, B1); PG8_BAR; PG8_SCHED;
	s_setprio 1
	s_waitcnt lgkmcnt(0)
	v_mfma_f32_16x16x32_bf16 v[62:65], v[140:143], v[200:203], 0
	v_mfma_f32_16x16x32_bf16 v[54:57], v[152:155], v[200:203], 0
	v_mfma_f32_16x16x32_bf16 v[46:49], v[140:143], v[208:211], 0
	v_mfma_f32_16x16x32_bf16 v[38:41], v[152:155], v[208:211], 0
	v_mfma_f32_16x16x32_bf16 v[30:33], v[140:143], v[216:219], 0
	v_mfma_f32_16x16x32_bf16 v[22:25], v[152:155], v[216:219], 0
	v_mfma_f32_16x16x32_bf16 v[14:17], v[140:143], v[224:227], 0
	v_mfma_f32_16x16x32_bf16 v[6:9], v[152:155], v[224:227], 0
	v_mfma_f32_16x16x32_bf16 v[62:65], v[148:151], v[204:207], v[62:65]
	v_mfma_f32_16x16x32_bf16 v[54:57], v[156:159], v[204:207], v[54:57]
	v_mfma_f32_16x16x32_bf16 v[46:49], v[148:151], v[212:215], v[46:49]
	v_mfma_f32_16x16x32_bf16 v[38:41], v[156:159], v[212:215], v[38:41]
	v_mfma_f32_16x16x32_bf16 v[30:33], v[148:151], v[220:223], v[30:33]
	v_mfma_f32_16x16x32_bf16 v[22:25], v[156:159], v[220:223], v[22:25]
	v_mfma_f32_16x16x32_bf16 v[14:17], v[148:151], v[228:231], v[14:17]
	v_mfma_f32_16x16x32_bf16 v[6:9], v[156:159], v[228:231], v[6:9]
	s_setprio 0
	s_setprio 1
	v_mfma_f32_16x16x32_bf16 v[58:61], v[164:167], v[200:203], 0
	v_mfma_f32_16x16x32_bf16 v[50:53], v[176:179], v[200:203], 0
	v_mfma_f32_16x16x32_bf16 v[42:45], v[164:167], v[208:211], 0
	v_mfma_f32_16x16x32_bf16 v[34:37], v[176:179], v[208:211], 0
	v_mfma_f32_16x16x32_bf16 v[26:29], v[164:167], v[216:219], 0
	v_mfma_f32_16x16x32_bf16 v[18:21], v[176:179], v[216:219], 0
	v_mfma_f32_16x16x32_bf16 v[10:13], v[164:167], v[224:227], 0
	v_mfma_f32_16x16x32_bf16 v[2:5], v[176:179], v[224:227], 0
	v_mfma_f32_16x16x32_bf16 v[58:61], v[172:175], v[204:207], v[58:61]
	v_mfma_f32_16x16x32_bf16 v[50:53], v[180:183], v[204:207], v[50:53]
	v_mfma_f32_16x16x32_bf16 v[42:45], v[172:175], v[212:215], v[42:45]
	v_mfma_f32_16x16x32_bf16 v[34:37], v[180:183], v[212:215], v[34:37]
	v_mfma_f32_16x16x32_bf16 v[26:29], v[172:175], v[220:223], v[26:29]
	v_mfma_f32_16x16x32_bf16 v[18:21], v[180:183], v[220:223], v[18:21]
	v_mfma_f32_16x16x32_bf16 v[10:13], v[172:175], v[228:231], v[10:13]
	v_mfma_f32_16x16x32_bf16 v[2:5], v[180:183], v[228:231], v[2:5]
	s_setprio 0
	s_barrier
	s_add_i32 s40, 0, 0x18000
	s_add_i32 s41, 0, 0x1c000
	v_add_u32_e32 v156, s40, v145
	v_add_u32_e32 v162, s41, v145
	ds_read_b128 v[140:143], v156
	ds_read_b128 v[148:151], v156 offset:1024
	ds_read_b128 v[152:155], v156 offset:2048
	ds_read_b128 v[156:159], v156 offset:3072
	ds_read_b128 v[164:167], v162
	ds_read_b128 v[172:175], v162 offset:1024
	ds_read_b128 v[176:179], v162 offset:2048
	ds_read_b128 v[180:183], v162 offset:3072
	s_add_u32 s18, s18, 0x80000
	s_addc_u32 s19, s19, 0
	s_mov_b32 m0, s25
	ds_read_b128 v[200:203], v147 offset:32768
	ds_read_b128 v[204:207], v147 offset:33792
	ds_read_b128 v[208:211], v147 offset:34816
	ds_read_b128 v[212:215], v147 offset:35840
	ds_read_b128 v[216:219], v147 offset:36864
	ds_read_b128 v[220:223], v147 offset:37888
	ds_read_b128 v[224:227], v147 offset:38912
	ds_read_b128 v[228:231], v147 offset:39936
	global_load_lds_dwordx4 v134, s[18:19]
	s_mov_b32 m0, s26
	s_nop 0
	global_load_lds_dwordx4 v132, s[18:19]
	s_waitcnt vmcnt(8)
	s_waitcnt lgkmcnt(0)
	s_barrier
	s_setprio 1
	s_waitcnt lgkmcnt(0)
	v_mfma_f32_16x16x32_bf16 v[126:129], v[140:143], v[200:203], v[126:129]
	v_mfma_f32_16x16x32_bf16 v[118:121], v[152:155], v[200:203], v[118:121]
	v_mfma_f32_16x16x32_bf16 v[110:113], v[140:143], v[208:211], v[110:113]
	v_mfma_f32_16x16x32_bf16 v[102:105], v[152:155], v[208:211], v[102:105]
	v_mfma_f32_16x16x32_bf16 v[94:97], v[140:143], v[216:219], v[94:97]
	v_mfma_f32_16x16x32_bf16 v[86:89], v[152:155], v[216:219], v[86:89]
	v_mfma_f32_16x16x32_bf16 v[78:81], v[140:143], v[224:227], v[78:81]
	v_mfma_f32_16x16x32_bf16 v[70:73], v[152:155], v[224:227], v[70:73]
	v_mfma_f32_16x16x32_bf16 v[126:129], v[148:151], v[204:207], v[126:129]
	v_mfma_f32_16x16x32_bf16 v[118:121], v[156:159], v[204:207], v[118:121]
	v_mfma_f32_16x16x32_bf16 v[110:113], v[148:151], v[212:215], v[110:113]
	v_mfma_f32_16x16x32_bf16 v[102:105], v[156:159], v[212:215], v[102:105]
	v_mfma_f32_16x16x32_bf16 v[94:97], v[148:151], v[220:223], v[94:97]
	v_mfma_f32_16x16x32_bf16 v[86:89], v[156:159], v[220:223], v[86:89]
	v_mfma_f32_16x16x32_bf16 v[78:81], v[148:151], v[228:231], v[78:81]
	v_mfma_f32_16x16x32_bf16 v[70:73], v[156:159], v[228:231], v[70:73]
	s_setprio 0
	s_setprio 1
	v_mfma_f32_16x16x32_bf16 v[122:125], v[164:167], v[200:203], v[122:125]
	v_mfma_f32_16x16x32_bf16 v[114:117], v[176:179], v[200:203], v[114:117]
	v_mfma_f32_16x16x32_bf16 v[106:109], v[164:167], v[208:211], v[106:109]
	v_mfma_f32_16x16x32_bf16 v[98:101], v[176:179], v[208:211], v[98:101]
	v_mfma_f32_16x16x32_bf16 v[90:93], v[164:167], v[216:219], v[90:93]
	v_mfma_f32_16x16x32_bf16 v[82:85], v[176:179], v[216:219], v[82:85]
	v_mfma_f32_16x16x32_bf16 v[74:77], v[164:167], v[224:227], v[74:77]
	v_mfma_f32_16x16x32_bf16 v[66:69], v[176:179], v[224:227], v[66:69]
	v_mfma_f32_16x16x32_bf16 v[122:125], v[172:175], v[204:207], v[122:125]
	v_mfma_f32_16x16x32_bf16 v[114:117], v[180:183], v[204:207], v[114:117]
	v_mfma_f32_16x16x32_bf16 v[106:109], v[172:175], v[212:215], v[106:109]
	v_mfma_f32_16x16x32_bf16 v[98:101], v[180:183], v[212:215], v[98:101]
	v_mfma_f32_16x16x32_bf16 v[90:93], v[172:175], v[220:223], v[90:93]
	v_mfma_f32_16x16x32_bf16 v[82:85], v[180:183], v[220:223], v[82:85]
	v_mfma_f32_16x16x32_bf16 v[74:77], v[172:175], v[228:231], v[74:77]
	v_mfma_f32_16x16x32_bf16 v[66:69], v[180:183], v[228:231], v[66:69]
	s_setprio 0
	s_barrier
; #define PG8_STAGE(bufoff, gbase, voff) do { _Pragma("unroll") for (int _i = 0; _i < 2; ++_i) \
;         __builtin_amdgcn_global_load_lds((const unsigned*)((const char*)(gbase) + (voff)[_i]), (PG8_LAS unsigned*)(lds + (bufoff) + ldsw + _i * 8192), 16, 0, 0); } while (0)
; #define PG8_LDA(dst, b, h) do { _Pragma("unroll") for (int m = 0; m < 4; ++m) _Pragma("unroll") for (int k = 0; k < 2; ++k) dst[m][k] = *(const PG8_LAS bf16x8*)(lds + PG8_SA(b, h) + aoff + m * 2048 + k * 1024); } while (0)
; #define PG8_LDB(dst, b, h) do { _Pragma("unroll") for (int n = 0; n < 2; ++n) _Pragma("unroll") for (int k = 0; k < 2; ++k) dst[n][k] = *(const PG8_LAS bf16x8*)(lds + PG8_SB(b, h) + boff + n * 2048 + k * 1024); } while (0)
; template <class Epi, class Sched, bool ALIGN_EPI = false, bool SP2 = false>
; __device__ __forceinline__ void gemm_phase(PG8_LAS unsigned char* lds, const Gemm g, const Sched& S, const Epi& E) {
;     ...
;         for (int t = 0; t < nt; t += 2) {
;             const bool last = (t == nt - 2);
;             const char* a1 = cA + (size_t)(t + 1) * kstep;
;             const char* a2 = last ? nA : cA + (size_t)(t + 2) * kstep; const char* b2 = last ? nB : cB + (size_t)(t + 2) * kstep;
;             const char* a3 = a2 + kstep; const char* b3 = b2 + kstep;
;             if (last && has_next) S.a_ready(nxt);
;             if constexpr (SP2) {
;             PG8_LDB(B0, 0, 0); PG8_LDB(B1, 0, 1); PG8_SCHED; PG8_LDA(At, 0, 0); PG8_STAGE(PG8_SA(1, 1), a1 + hstep, voffA);
;             PG8_WAIT_V(8); PG8_WAIT_L(0); PG8_BAR; PG8_MMA(0, 0, At, B0); PG8_MMA(0, 1, At, B1); PG8_BAR; PG8_SCHED;
;             PG8_LDA(At, 0, 1); PG8_STAGE(PG8_SB(0, 0), b2, voffB); PG8_STAGE(PG8_SB(0, 1), b2 + hstep, voffB); PG8_STAGE(PG8_SA(0, 0), a2, voffA);
;             PG8_WAIT_V(8); PG8_WAIT_L(0); PG8_BAR; PG8_MMA(1, 0, At, B0); PG8_MMA(1, 1, At, B1); PG8_BAR; PG8_SCHED;
;             PG8_LDB(B0, 1, 0); PG8_LDB(B1, 1, 1); PG8_SCHED; PG8_LDA(At, 1, 0); PG8_STAGE(PG8_SA(0, 1), a2 + hstep, voffA);
;             PG8_WAIT_V(8); PG8_WAIT_L(0); PG8_BAR; PG8_MMA(0, 0, At, B0); PG8_MMA(0, 1, At, B1); PG8_BAR; PG8_SCHED;
;             PG8_LDA(At, 1, 1); PG8_STAGE(PG8_SB(1, 0), b3, voffB); PG8_STAGE(PG8_SB(1, 1), b3 + hstep, voffB); PG8_STAGE(PG8_SA(1, 0), a3, voffA);
;             PG8_WAIT_V(8); PG8_WAIT_L(0); PG8_BAR; PG8_MMA(1, 0, At, B0); PG8_MMA(1, 1, At, B1); PG8_BAR; PG8_SCHED;
	s_add_i32 s18, s40, s22
	s_mov_b32 m0, s18
	ds_read_b128 v[200:203], v147 offset:49152
	ds_read_b128 v[204:207], v147 offset:50176
	ds_read_b128 v[208:211], v147 offset:51200
	ds_read_b128 v[212:215], v147 offset:52224
	ds_read_b128 v[216:219], v147 offset:53248
	ds_read_b128 v[220:223], v147 offset:54272
	ds_read_b128 v[224:227], v147 offset:55296
	ds_read_b128 v[228:231], v147 offset:56320
	global_load_lds_dwordx4 v0, s[48:49]
	s_add_i32 m0, s18, 0x2000
	s_add_u32 s16, s16, 0x80080
	s_addc_u32 s17, s17, 0
	s_add_i32 s18, s41, s22
	global_load_lds_dwordx4 v130, s[48:49]
	s_mov_b32 m0, s18
	s_nop 0
	global_load_lds_dwordx4 v0, s[16:17]
	s_add_i32 m0, s18, 0x2000
	s_nop 0
	global_load_lds_dwordx4 v130, s[16:17]
	s_mov_b32 m0, s27
	s_nop 0
	global_load_lds_dwordx4 v134, s[50:51]
	s_mov_b32 m0, s28
	s_nop 0
	global_load_lds_dwordx4 v132, s[50:51]
	s_waitcnt vmcnt(8)
	s_waitcnt lgkmcnt(0)
	s_barrier
	s_setprio 1
	s_waitcnt lgkmcnt(0)
	v_mfma_f32_16x16x32_bf16 v[62:65], v[140:143], v[200:203], v[62:65]
	v_mfma_f32_16x16x32_bf16 v[54:57], v[152:155], v[200:203], v[54:57]
	v_mfma_f32_16x16x32_bf16 v[46:49], v[140:143], v[208:211], v[46:49]
	v_mfma_f32_16x16x32_bf16 v[38:41], v[152:155], v[208:211], v[38:41]
	v_mfma_f32_16x16x32_bf16 v[30:33], v[140:143], v[216:219], v[30:33]
	v_mfma_f32_16x16x32_bf16 v[22:25], v[152:155], v[216:219], v[22:25]
	v_mfma_f32_16x16x32_bf16 v[14:17], v[140:143], v[224:227], v[14:17]
	v_mfma_f32_16x16x32_bf16 v[6:9], v[152:155], v[224:227], v[6:9]
	v_mfma_f32_16x16x32_bf16 v[62:65], v[148:151], v[204:207], v[62:65]
	v_mfma_f32_16x16x32_bf16 v[54:57], v[156:159], v[204:207], v[54:57]
	v_mfma_f32_16x16x32_bf16 v[46:49], v[148:151], v[212:215], v[46:49]
	v_mfma_f32_16x16x32_bf16 v[38:41], v[156:159], v[212:215], v[38:41]
	v_mfma_f32_16x16x32_bf16 v[30:33], v[148:151], v[220:223], v[30:33]
	v_mfma_f32_16x16x32_bf16 v[22:25], v[156:159], v[220:223], v[22:25]
	v_mfma_f32_16x16x32_bf16 v[14:17], v[148:151], v[228:231], v[14:17]
	v_mfma_f32_16x16x32_bf16 v[6:9], v[156:159], v[228:231], v[6:9]
	s_setprio 0
	s_setprio 1
	v_mfma_f32_16x16x32_bf16 v[58:61], v[164:167], v[200:203], v[58:61]
	v_mfma_f32_16x16x32_bf16 v[50:53], v[176:179], v[200:203], v[50:53]
	v_mfma_f32_16x16x32_bf16 v[42:45], v[164:167], v[208:211], v[42:45]
	v_mfma_f32_16x16x32_bf16 v[34:37], v[176:179], v[208:211], v[34:37]
	v_mfma_f32_16x16x32_bf16 v[26:29], v[164:167], v[216:219], v[26:29]
	v_mfma_f32_16x16x32_bf16 v[18:21], v[176:179], v[216:219], v[18:21]
	v_mfma_f32_16x16x32_bf16 v[10:13], v[164:167], v[224:227], v[10:13]
	v_mfma_f32_16x16x32_bf16 v[2:5], v[176:179], v[224:227], v[2:5]
	v_mfma_f32_16x16x32_bf16 v[58:61], v[172:175], v[204:207], v[58:61]
	v_mfma_f32_16x16x32_bf16 v[50:53], v[180:183], v[204:207], v[50:53]
	v_mfma_f32_16x16x32_bf16 v[42:45], v[172:175], v[212:215], v[42:45]
	v_mfma_f32_16x16x32_bf16 v[34:37], v[180:183], v[212:215], v[34:37]
	v_mfma_f32_16x16x32_bf16 v[26:29], v[172:175], v[220:223], v[26:29]
	v_mfma_f32_16x16x32_bf16 v[18:21], v[180:183], v[220:223], v[18:21]
	v_mfma_f32_16x16x32_bf16 v[10:13], v[172:175], v[228:231], v[10:13]
	v_mfma_f32_16x16x32_bf16 v[2:5], v[180:183], v[228:231], v[2:5]
	s_setprio 0
	s_barrier
	s_add_i32 s37, s37, 2
	s_add_u32 s14, s14, 0x100
	s_addc_u32 s15, s15, 0
	s_add_u32 s35, s35, 0x100
	s_addc_u32 s36, s36, 0
	s_cmp_gt_u32 s37, 29
